# speedup vs baseline: 1.0050x; 1.0050x over previous
; #define LAS __attribute__((address_space(3)))
; template <bool PASS2>
; __device__ __forceinline__ void ssm_fast_item(const Ctx& C, int item) {
;     const int lane = C.lane, l32 = lane & 31, hf = lane >> 5;
;     const int ch = (item & 2048) ? (NCH - 1) - (item & (NCH - 1)) : (item & (NCH - 1)), g = (item >> 5) & 31, b = item >> 10;
;     LAS unsigned* shw = (LAS unsigned*)C.lds + C.wave * SSM_WAVE_FLOATS;
;     const bf16* PROJ = WSP(const bf16, WS_PROJ);
;     const float ar = WSP(const float, WS_ABAR)[2 * (g * 64 + lane)], ai = WSP(const float, WS_ABAR)[2 * (g * 64 + lane) + 1];
;     bf16x8 bfr[4];
; #pragma unroll
;     for (int nb = 0; nb < 4; ++nb) {
;         const int col = 32 * nb + l32;
;         const float* src = (col < 64 ? WSP(const float, WS_BBRE) + (size_t)(g * 64 + col) * 16 : WSP(const float, WS_BBIM) + (size_t)(g * 64 + col - 64) * 16) + 8 * hf;
;         const f32x4 x0 = *(const f32x4*)src, x1 = *(const f32x4*)(src + 4);
;         bfr[nb] = pack8(x0.x, x0.y, x0.z, x0.w, x1.x, x1.y, x1.z, x1.w);
;     }
;     bf16x8 cfr[8];
;     if (PASS2) {
; #pragma unroll
;         for (int kk = 0; kk < 8; ++kk) {
;             f32x4 cr = {0.f, 0.f, 0.f, 0.f}, ci = cr;
;             if (l32 < 16) { cr = *(const f32x4*)(C.in[9] + (size_t)(g * 16 + l32) * 64 + 8 * kk + 4 * hf); ci = *(const f32x4*)(C.in[10] + (size_t)(g * 16 + l32) * 64 + 8 * kk + 4 * hf); }
;             cfr[kk] = pack8(cr.x, -ci.x, cr.y, -ci.y, cr.z, -ci.z, cr.w, -ci.w);
;         }
;     }
;     float sr = 0.f, si = 0.f;
;     float* chs = WSP(float, WS_CHS) + (size_t)((b * 32 + g) * NCH) * 128;
;     if (PASS2) {
;         const float pr = WSP(const float, WS_APOW)[2 * (g * 64 + lane)], pi = WSP(const float, WS_APOW)[2 * (g * 64 + lane) + 1];
; __device__ __forceinline__ void ssm_fast_pass2(const Ctx& C) { for (int it = C.gw; it < 4 * 32 * NCH; it += C.NGW) ssm_fast_item<true>(C, it); }
.LBB0_445:
	s_or_b64 exec, exec, s[4:5]
	s_andn2_b64 vcc, exec, s[0:1]
	v_and_b32_e32 v201, 31, v182
	s_cbranch_vccnz .LBB0_477
	v_mov_b32_e32 v129, 0
	v_and_b32_e32 v0, 32, v196
	v_mov_b32_e32 v1, v129
	s_mul_i32 s4, s90, 0x4200
	s_add_u32 s0, s78, 0x1a400000
	v_lshl_add_u64 v[0:1], s[78:79], 0, v[0:1]
	s_mov_b64 s[2:3], 0x1a410000
	v_lshrrev_b32_e32 v3, 5, v196
	s_addc_u32 s1, s79, 0
	v_lshl_add_u64 v[130:131], v[0:1], 0, s[2:3]
	s_add_i32 s2, s4, 0
	v_lshlrev_b32_e32 v6, 2, v196
	v_lshlrev_b32_e32 v2, 2, v3
	v_mov_b32_e32 v7, s2
	s_waitcnt vmcnt(2)
	v_lshl_add_u32 v8, v201, 2, s2
	v_add_u32_e32 v141, s2, v6
	s_movk_i32 s2, 0x110
	v_lshlrev_b32_e32 v128, 3, v3
	s_add_u32 s4, s78, 0x1a404000
	v_mad_u32_u24 v9, v201, s2, v7
	v_or_b32_e32 v7, 8, v2
	s_mov_b64 s[8:9], 0x1a430000
	s_addc_u32 s5, s79, 0
	v_mul_u32_u24_e32 v10, 0x110, v7
	v_lshl_add_u64 v[146:147], v[0:1], 0, s[8:9]
	v_lshl_add_u64 v[0:1], s[78:79], 0, v[128:129]
	s_mov_b64 s[8:9], 0x12000000
	v_mov_b32_e32 v7, v129
	v_lshlrev_b32_e32 v4, 4, v3
	v_mov_b32_e32 v5, v129
	v_mul_u32_u24_e32 v3, 0x440, v3
	v_lshl_add_u64 v[148:149], v[0:1], 0, s[8:9]
	v_lshl_add_u64 v[0:1], s[78:79], 0, v[6:7]
	s_mov_b64 s[8:9], 0x1a500700
	s_add_u32 s7, s78, 0x1a500100
	v_or_b32_e32 v137, 32, v201
	s_mov_b32 s3, 0
	v_cmp_gt_u32_e32 vcc, 16, v201
	v_lshlrev_b32_e32 v139, 6, v201
	v_lshl_add_u64 v[132:133], s[10:11], 0, v[4:5]
	v_lshl_add_u64 v[134:135], s[12:13], 0, v[4:5]
	v_lshl_add_u64 v[144:145], s[14:15], 0, v[4:5]
	v_lshl_add_u64 v[150:151], v[0:1], 0, s[8:9]
	s_addc_u32 s16, s79, 0
	s_mov_b64 s[8:9], 0x800
	s_mov_b64 s[10:11], 0x200
	v_lshlrev_b32_e32 v152, 1, v128
	v_lshlrev_b32_e32 v154, 1, v2
	v_add_u32_e32 v143, v8, v3
	v_add_u32_e32 v177, v8, v10
	v_add_u32_e32 v178, v9, v4
	v_readfirstlane_b32 s27, v182
	s_nop 3
	s_lshr_b32 s27, s27, 6
	s_cmp_lt_u32 s27, 4
	s_cbranch_scc1 .Lstag_ssm2
	s_sleep 30
